# added: diff-attn component-1 epilogue OD bf16 rows restaged through LDS and stored row-contiguous (4 rows x 256B per store), on top of O1 and OM row-contiguous stores
# speedup vs baseline: 1.0121x; 1.0121x over previous
; __device__ __forceinline__ u32x4 pack8(const f32x4 a, const f32x4 b) { u32x4 w; w.x = cvt_pk(a[0], a[1]); w.y = cvt_pk(a[2], a[3]); w.z = cvt_pk(b[0], b[1]); w.w = cvt_pk(b[2], b[3]); return w; }
; __device__ __forceinline__ float sq4(f32x4 v) { return (v[0] * v[0] + v[1] * v[1]) + (v[2] * v[2] + v[3] * v[3]); }
; template <int MODE> __device__ __forceinline__ void attn_epilogue(char* lds, const att::f32x16 (&o)[4], const float (&rli)[16], float* o1, bf16raw* ob, float lam, float post, const float* gs) {
;     ...
;         float s = 0.f;
; #pragma unroll 4
;         for (int j = 0; j < 16; ++j) { const f32x4 x = *(const f32x4*)(sr + 4 * j), y = *(const f32x4*)(o1 + goff + 4 * j); const f32x4 v = y - x * lam; s += ep::sq4(v); *(f32x4*)(sr + 4 * j) = v; }
;         s += __shfl_xor(s, 32);
;         const float rs = post / sqrtf(s * (1.0f / 128.0f) + 1e-5f);
; #pragma unroll 4
;         for (int j = 0; j < 8; ++j) { const f32x4 g0 = *(const f32x4*)(gs + 64 * hi + 8 * j), g1 = *(const f32x4*)(gs + 64 * hi + 8 * j + 4);
;             *(ep::u32x4*)(ob + boff + 8 * j) = ep::pack8(*(const f32x4*)(sr + 8 * j) * g0 * rs, *(const f32x4*)(sr + 8 * j + 4) * g1 * rs); }
.LBB0_780:
	global_load_dwordx4 v[12:15], v[4:5], off offset:-32
	global_load_dwordx4 v[16:19], v[4:5], off offset:-16
	global_load_dwordx4 v[20:23], v[4:5], off
	global_load_dwordx4 v[24:27], v[4:5], off offset:16
	v_add_u32_e32 v11, s0, v10
	ds_read_b128 v[28:31], v11
	ds_read_b128 v[32:35], v11 offset:16
	ds_read_b128 v[36:39], v11 offset:32
	ds_read_b128 v[40:43], v11 offset:48
	v_xor_b32_e32 v173, 0x80000000, v131
	s_add_i32 s0, s0, 64
	v_lshl_add_u64 v[4:5], v[4:5], 0, 64
	s_cmpk_eq_i32 s0, 0x100
	s_waitcnt vmcnt(3) lgkmcnt(3)
	v_pk_fma_f32 v[14:15], v[172:173], v[30:31], v[14:15]
	v_pk_fma_f32 v[12:13], v[168:169], v[28:29], v[12:13] neg_lo:[1,0,0] neg_hi:[1,0,0]
	s_waitcnt vmcnt(2) lgkmcnt(2)
	v_pk_fma_f32 v[18:19], v[172:173], v[34:35], v[18:19]
	v_pk_fma_f32 v[16:17], v[168:169], v[32:33], v[16:17] neg_lo:[1,0,0] neg_hi:[1,0,0]
	s_waitcnt vmcnt(1) lgkmcnt(1)
	v_pk_fma_f32 v[22:23], v[172:173], v[38:39], v[22:23]
	v_pk_fma_f32 v[20:21], v[168:169], v[36:37], v[20:21] neg_lo:[1,0,0] neg_hi:[1,0,0]
	s_waitcnt vmcnt(0) lgkmcnt(0)
	v_pk_fma_f32 v[26:27], v[172:173], v[42:43], v[26:27]
	v_pk_fma_f32 v[24:25], v[168:169], v[40:41], v[24:25] neg_lo:[1,0,0] neg_hi:[1,0,0]
	v_pk_mul_f32 v[8:9], v[14:15], v[14:15]
	v_pk_mul_f32 v[28:29], v[12:13], v[12:13]
	ds_write_b128 v11, v[12:15]
	v_pk_mul_f32 v[12:13], v[18:19], v[18:19]
	v_pk_mul_f32 v[14:15], v[16:17], v[16:17]
	ds_write_b128 v11, v[16:19] offset:16
	v_pk_mul_f32 v[16:17], v[22:23], v[22:23]
	v_pk_mul_f32 v[18:19], v[20:21], v[20:21]
	ds_write_b128 v11, v[20:23] offset:32
	v_pk_mul_f32 v[20:21], v[26:27], v[26:27]
	v_pk_mul_f32 v[22:23], v[24:25], v[24:25]
	ds_write_b128 v11, v[24:27] offset:48
	v_pk_mov_b32 v[24:25], v[28:29], v[8:9] op_sel:[1,0]
	v_mov_b32_e32 v29, v9
	v_pk_mov_b32 v[8:9], v[14:15], v[12:13] op_sel:[1,0]
	v_mov_b32_e32 v15, v13
	v_pk_mov_b32 v[12:13], v[18:19], v[16:17] op_sel:[1,0]
	v_mov_b32_e32 v19, v17
	v_pk_mov_b32 v[16:17], v[22:23], v[20:21] op_sel:[1,0]
	v_mov_b32_e32 v23, v21
	v_pk_add_f32 v[20:21], v[24:25], v[28:29]
	v_pk_add_f32 v[8:9], v[8:9], v[14:15]
	v_add_f32_e32 v11, v20, v21
	v_pk_add_f32 v[12:13], v[12:13], v[18:19]
	v_add_f32_e32 v8, v8, v9
	v_add_f32_e32 v7, v7, v11
	v_pk_add_f32 v[14:15], v[16:17], v[22:23]
	v_add_f32_e32 v9, v12, v13
	v_add_f32_e32 v7, v7, v8
	v_add_f32_e32 v12, v14, v15
	v_add_f32_e32 v7, v7, v9
	v_add_f32_e32 v7, v7, v12
	s_cbranch_scc0 .LBB0_780
	ds_bpermute_b32 v4, v130, v7
	v_mov_b32_e32 v5, 0x3727c5ac
	v_lshlrev_b32_e32 v160, 2, v6
	v_lshl_add_u64 v[2:3], v[2:3], 0, s[56:57]
	s_waitcnt lgkmcnt(0)
	v_add_f32_e32 v4, v7, v4
	v_fmamk_f32 v4, v4, 0x3c000000, v5
	v_mul_f32_e32 v5, 0x4f800000, v4
	v_cmp_gt_f32_e32 vcc, s3, v4
	s_nop 1
	v_cndmask_b32_e32 v4, v4, v5, vcc
	v_sqrt_f32_e32 v5, v4
	s_nop 0
	v_add_u32_e32 v7, -1, v5
	v_add_u32_e32 v8, 1, v5
	v_fma_f32 v9, -v7, v5, v4
	v_fma_f32 v11, -v8, v5, v4
	v_cmp_ge_f32_e64 s[0:1], 0, v9
	s_nop 1
	v_cndmask_b32_e64 v5, v5, v7, s[0:1]
	v_cmp_lt_f32_e64 s[0:1], 0, v11
	s_nop 1
	v_cndmask_b32_e64 v5, v5, v8, s[0:1]
	v_mul_f32_e32 v7, 0x37800000, v5
	v_cndmask_b32_e32 v5, v5, v7, vcc
	v_cmp_class_f32_e32 vcc, v4, v188
	s_nop 1
	v_cndmask_b32_e32 v4, v5, v4, vcc
	v_div_scale_f32 v5, s[0:1], v4, v4, v191
	v_rcp_f32_e32 v7, v5
	s_add_u32 s0, s9, s22
	s_addc_u32 s1, s8, s23
	v_fma_f32 v8, -v5, v7, 1.0
	v_fmac_f32_e32 v7, v8, v7
	v_div_scale_f32 v8, vcc, v191, v4, v191
	v_mul_f32_e32 v9, v8, v7
	v_fma_f32 v11, -v5, v9, v8
	v_fmac_f32_e32 v9, v11, v7
	v_fma_f32 v5, -v5, v9, v8
	v_div_fmas_f32 v5, v5, v7, v9
	v_lshl_add_u64 v[6:7], s[0:1], 0, v[160:161]
	v_lshlrev_b32_e32 v160, 7, v66
	v_div_fixup_f32 v4, v5, v4, v191
	v_lshl_add_u64 v[2:3], v[2:3], 0, v[160:161]
	v_mov_b32_e32 v5, v4
	v_mov_b32_e32 v8, v4
	v_mov_b32_e32 v9, v4
	v_lshl_add_u64 v[2:3], s[20:21], 0, v[2:3]
	v_mov_b32_e32 v252, v10
	s_mov_b64 s[0:1], 0
; __device__ __forceinline__ u32x4 pack8(const f32x4 a, const f32x4 b) { u32x4 w; w.x = cvt_pk(a[0], a[1]); w.y = cvt_pk(a[2], a[3]); w.z = cvt_pk(b[0], b[1]); w.w = cvt_pk(b[2], b[3]); return w; }
; template <int MODE> __device__ __forceinline__ void attn_epilogue(char* lds, const att::f32x16 (&o)[4], const float (&rli)[16], float* o1, bf16raw* ob, float lam, float post, const float* gs) {
;     ...
; #pragma unroll 4
;         for (int j = 0; j < 8; ++j) { const f32x4 g0 = *(const f32x4*)(gs + 64 * hi + 8 * j), g1 = *(const f32x4*)(gs + 64 * hi + 8 * j + 4);
;             *(ep::u32x4*)(ob + boff + 8 * j) = ep::pack8(*(const f32x4*)(sr + 8 * j) * g0 * rs, *(const f32x4*)(sr + 8 * j + 4) * g1 * rs); }
.LBB0_782:
	v_lshl_add_u64 v[28:29], v[6:7], 0, s[0:1]
	global_load_dwordx4 v[12:15], v[28:29], off
	global_load_dwordx4 v[16:19], v[28:29], off offset:16
	ds_read_b128 v[20:23], v10
	ds_read_b128 v[24:27], v10 offset:16
	s_add_u32 s0, s0, 0x80
	s_addc_u32 s1, s1, 0
	s_cmpk_lg_i32 s0, 0x100
	s_waitcnt vmcnt(1) lgkmcnt(1)
	v_pk_mul_f32 v[14:15], v[14:15], v[22:23]
	v_pk_mul_f32 v[12:13], v[12:13], v[20:21]
	s_waitcnt vmcnt(0) lgkmcnt(0)
	v_pk_mul_f32 v[18:19], v[18:19], v[26:27]
	v_pk_mul_f32 v[16:17], v[16:17], v[24:25]
	v_pk_mul_f32 v[14:15], v[8:9], v[14:15]
	v_pk_mul_f32 v[12:13], v[4:5], v[12:13]
	v_pk_mul_f32 v[18:19], v[8:9], v[18:19]
	v_pk_mul_f32 v[16:17], v[4:5], v[16:17]
	v_cvt_pk_bf16_f32 v12, v12, v13
	v_cvt_pk_bf16_f32 v13, v14, v15
	v_cvt_pk_bf16_f32 v14, v16, v17
	v_cvt_pk_bf16_f32 v15, v18, v19
	ds_write_b128 v252, v[12:15]
	global_load_dwordx4 v[12:15], v[28:29], off offset:32
	s_nop 0
	global_load_dwordx4 v[16:19], v[28:29], off offset:48
	ds_read_b128 v[20:23], v10 offset:32
	ds_read_b128 v[24:27], v10 offset:48
	s_waitcnt vmcnt(1) lgkmcnt(1)
	v_pk_mul_f32 v[14:15], v[14:15], v[22:23]
	v_pk_mul_f32 v[12:13], v[12:13], v[20:21]
	s_waitcnt vmcnt(0) lgkmcnt(0)
	v_pk_mul_f32 v[18:19], v[18:19], v[26:27]
	v_pk_mul_f32 v[16:17], v[16:17], v[24:25]
	v_pk_mul_f32 v[14:15], v[8:9], v[14:15]
	v_pk_mul_f32 v[12:13], v[4:5], v[12:13]
	v_pk_mul_f32 v[18:19], v[8:9], v[18:19]
	v_pk_mul_f32 v[16:17], v[4:5], v[16:17]
	v_cvt_pk_bf16_f32 v12, v12, v13
	v_cvt_pk_bf16_f32 v13, v14, v15
	v_cvt_pk_bf16_f32 v14, v16, v17
	v_cvt_pk_bf16_f32 v15, v18, v19
	ds_write_b128 v252, v[12:15] offset:32
	global_load_dwordx4 v[12:15], v[28:29], off offset:64
	s_nop 0
	global_load_dwordx4 v[16:19], v[28:29], off offset:80
	ds_read_b128 v[20:23], v10 offset:64
	ds_read_b128 v[24:27], v10 offset:80
	s_waitcnt vmcnt(1) lgkmcnt(1)
	v_pk_mul_f32 v[14:15], v[14:15], v[22:23]
	v_pk_mul_f32 v[12:13], v[12:13], v[20:21]
	s_waitcnt vmcnt(0) lgkmcnt(0)
	v_pk_mul_f32 v[18:19], v[18:19], v[26:27]
	v_pk_mul_f32 v[16:17], v[16:17], v[24:25]
	v_pk_mul_f32 v[14:15], v[8:9], v[14:15]
	v_pk_mul_f32 v[12:13], v[4:5], v[12:13]
	v_pk_mul_f32 v[18:19], v[8:9], v[18:19]
	v_pk_mul_f32 v[16:17], v[4:5], v[16:17]
	v_cvt_pk_bf16_f32 v12, v12, v13
	v_cvt_pk_bf16_f32 v13, v14, v15
	v_cvt_pk_bf16_f32 v14, v16, v17
	v_cvt_pk_bf16_f32 v15, v18, v19
	ds_write_b128 v252, v[12:15] offset:64
	global_load_dwordx4 v[12:15], v[28:29], off offset:96
	s_nop 0
	global_load_dwordx4 v[16:19], v[28:29], off offset:112
	ds_read_b128 v[20:23], v10 offset:96
	ds_read_b128 v[24:27], v10 offset:112
	v_add_u32_e32 v10, 0x80, v10
	s_waitcnt vmcnt(1) lgkmcnt(1)
	v_pk_mul_f32 v[14:15], v[14:15], v[22:23]
	v_pk_mul_f32 v[12:13], v[12:13], v[20:21]
	s_waitcnt vmcnt(0) lgkmcnt(0)
	v_pk_mul_f32 v[18:19], v[18:19], v[26:27]
	v_pk_mul_f32 v[16:17], v[16:17], v[24:25]
	v_pk_mul_f32 v[14:15], v[8:9], v[14:15]
	v_pk_mul_f32 v[12:13], v[4:5], v[12:13]
	v_pk_mul_f32 v[18:19], v[8:9], v[18:19]
	v_pk_mul_f32 v[16:17], v[4:5], v[16:17]
	v_cvt_pk_bf16_f32 v12, v12, v13
	v_cvt_pk_bf16_f32 v13, v14, v15
	v_cvt_pk_bf16_f32 v14, v16, v17
	v_cvt_pk_bf16_f32 v15, v18, v19
	ds_write_b128 v252, v[12:15] offset:96
	v_lshl_add_u64 v[2:3], v[2:3], 0, 64
	v_add_u32_e32 v252, 0x80, v252
	s_cbranch_scc1 .LBB0_782
	s_waitcnt lgkmcnt(0)
	v_and_b32_e32 v244, 15, v190
	v_lshrrev_b32_e32 v245, 4, v190
	v_mul_u32_u24_e32 v246, 0x210, v245
	v_lshrrev_b32_e32 v247, 3, v244
	v_lshl_add_u32 v246, v247, 8, v246
	v_and_b32_e32 v247, 7, v244
	v_lshl_add_u32 v246, v247, 5, v246
	v_add_u32_e32 v246, v67, v246
	v_lshlrev_b32_e32 v248, 12, v84
	v_lshl_add_u32 v248, v66, 7, v248
	v_add_u32_e32 v248, 0x80, v248
	v_sub_co_u32_e32 v250, vcc, v2, v248
	s_nop 1
	v_subbrev_co_u32_e32 v251, vcc, 0, v3, vcc
	v_lshlrev_b32_e32 v248, 12, v245
	v_lshl_add_u32 v248, v244, 4, v248
	v_mov_b32_e32 v249, 0
	v_lshl_add_u64 v[250:251], v[250:251], 0, v[248:249]
	s_mov_b32 s98, 0x4000
	s_mov_b32 s99, 0
	ds_read_b128 v[12:15], v246
	ds_read_b128 v[16:19], v246 offset:2112
	ds_read_b128 v[20:23], v246 offset:4224
	ds_read_b128 v[24:27], v246 offset:6336
	s_waitcnt lgkmcnt(3)
	global_store_dwordx4 v[250:251], v[12:15], off offset:-32
	s_nop 0
	v_lshl_add_u64 v[250:251], v[250:251], 0, s[98:99]
	s_waitcnt lgkmcnt(2)
	global_store_dwordx4 v[250:251], v[16:19], off offset:-32
	s_nop 0
	v_lshl_add_u64 v[250:251], v[250:251], 0, s[98:99]
	s_waitcnt lgkmcnt(1)
	global_store_dwordx4 v[250:251], v[20:23], off offset:-32
	s_nop 0
	v_lshl_add_u64 v[250:251], v[250:251], 0, s[98:99]
	s_waitcnt lgkmcnt(0)
	global_store_dwordx4 v[250:251], v[24:27], off offset:-32
	s_nop 0
	v_lshl_add_u64 v[250:251], v[250:251], 0, s[98:99]
	ds_read_b128 v[12:15], v246 offset:8448
	ds_read_b128 v[16:19], v246 offset:10560
	ds_read_b128 v[20:23], v246 offset:12672
	ds_read_b128 v[24:27], v246 offset:14784
	s_waitcnt lgkmcnt(3)
	global_store_dwordx4 v[250:251], v[12:15], off offset:-32
	s_nop 0
	v_lshl_add_u64 v[250:251], v[250:251], 0, s[98:99]
	s_waitcnt lgkmcnt(2)
	global_store_dwordx4 v[250:251], v[16:19], off offset:-32
	s_nop 0
	v_lshl_add_u64 v[250:251], v[250:251], 0, s[98:99]
	s_waitcnt lgkmcnt(1)
	global_store_dwordx4 v[250:251], v[20:23], off offset:-32
	s_nop 0
	v_lshl_add_u64 v[250:251], v[250:251], 0, s[98:99]
	s_waitcnt lgkmcnt(0)
	global_store_dwordx4 v[250:251], v[24:27], off offset:-32
	s_nop 0
	v_lshl_add_u64 v[250:251], v[250:251], 0, s[98:99]
	s_add_i32 s4, s4, s73
	s_add_i32 s26, s26, s27
	s_add_i32 s28, s28, s29
	s_cmpk_gt_i32 s4, 0x1ff
	s_barrier
	s_cbranch_scc0 .LBB0_755
	s_branch .LBB0_785
